# non-aligned unit epilogues on all 14 GEMM instances + peel, packed SwiGLU, div trim, fragment-read hoist
# speedup vs baseline: 1.0050x; 1.0050x over previous
.LBB0_544:
	v_lshl_or_b32 v148, s53, 8, v144
	v_lshl_add_u32 v150, s26, 8, v142
	v_ashrrev_i32_e32 v149, 31, v148
	v_ashrrev_i32_e32 v151, 31, v150
	v_lshl_add_u64 v[148:149], v[148:149], 1, s[78:79]
	v_lshlrev_b64 v[152:153], 13, v[150:151]
	v_lshl_add_u64 v[152:153], v[148:149], 0, v[152:153]
	v_cvt_pk_bf16_f32 v62, v62, v63
	v_cvt_pk_bf16_f32 v63, v64, v65
	v_cvt_pk_bf16_f32 v64, v58, v59
	v_add_co_u32_e32 v58, vcc, s49, v152
	v_cvt_pk_bf16_f32 v70, v70, v71
	v_cvt_pk_bf16_f32 v71, v72, v73
	v_cvt_pk_bf16_f32 v72, v66, v67
	v_lshl_add_u64 v[66:67], v[152:153], 0, s[10:11]
	v_addc_co_u32_e32 v59, vcc, 0, v153, vcc
	v_cvt_pk_bf16_f32 v46, v46, v47
	v_cvt_pk_bf16_f32 v47, v48, v49
	v_cvt_pk_bf16_f32 v48, v42, v43
	v_cvt_pk_bf16_f32 v49, v44, v45
	global_store_dwordx4 v[66:67], v[46:49], off offset:256
	v_cvt_pk_bf16_f32 v110, v110, v111
	v_cvt_pk_bf16_f32 v111, v112, v113
	v_add_co_u32_e32 v48, vcc, s50, v152
	v_cvt_pk_bf16_f32 v112, v106, v107
	v_or_b32_e32 v106, 16, v150
	v_lshl_add_u64 v[46:47], v[152:153], 0, s[12:13]
	v_addc_co_u32_e32 v49, vcc, 0, v153, vcc
	v_cvt_pk_bf16_f32 v30, v30, v31
	v_cvt_pk_bf16_f32 v31, v32, v33
	v_cvt_pk_bf16_f32 v32, v26, v27
	v_cvt_pk_bf16_f32 v33, v28, v29
	v_ashrrev_i32_e32 v107, 31, v106
	v_cvt_pk_bf16_f32 v94, v94, v95
	v_cvt_pk_bf16_f32 v95, v96, v97
	v_cvt_pk_bf16_f32 v96, v90, v91
	v_or_b32_e32 v90, 32, v150
	global_store_dwordx4 v[46:47], v[30:33], off offset:256
	v_cvt_pk_bf16_f32 v113, v108, v109
	v_lshlrev_b64 v[106:107], 13, v[106:107]
	v_add_co_u32_e32 v32, vcc, s51, v152
	v_ashrrev_i32_e32 v91, 31, v90
	v_cvt_pk_bf16_f32 v78, v78, v79
	v_cvt_pk_bf16_f32 v79, v80, v81
	v_cvt_pk_bf16_f32 v80, v74, v75
	v_or_b32_e32 v74, 48, v150
	v_lshl_add_u64 v[30:31], v[152:153], 0, s[16:17]
	v_addc_co_u32_e32 v33, vcc, 0, v153, vcc
	v_cvt_pk_bf16_f32 v14, v14, v15
	v_cvt_pk_bf16_f32 v15, v16, v17
	v_cvt_pk_bf16_f32 v16, v10, v11
	v_cvt_pk_bf16_f32 v17, v12, v13
	global_store_dwordx4 v[152:153], v[110:113], off offset:256
	v_cvt_pk_bf16_f32 v97, v92, v93
	v_lshlrev_b64 v[90:91], 13, v[90:91]
	v_lshl_add_u64 v[110:111], v[148:149], 0, v[106:107]
	v_ashrrev_i32_e32 v75, 31, v74
	global_store_dwordx4 v[30:31], v[14:17], off offset:256
	global_store_dwordx4 v[110:111], v[94:97], off offset:256
	v_cvt_pk_bf16_f32 v81, v76, v77
	v_add_co_u32_e32 v16, vcc, s52, v152
	v_lshl_add_u64 v[94:95], v[148:149], 0, v[90:91]
	v_lshlrev_b64 v[74:75], 13, v[74:75]
	v_addc_co_u32_e32 v17, vcc, 0, v153, vcc
	v_cvt_pk_bf16_f32 v126, v126, v127
	v_cvt_pk_bf16_f32 v127, v128, v129
	v_cvt_pk_bf16_f32 v128, v122, v123
	v_cvt_pk_bf16_f32 v129, v124, v125
	v_cvt_pk_bf16_f32 v106, v118, v119
	v_cvt_pk_bf16_f32 v107, v120, v121
	v_cvt_pk_bf16_f32 v108, v114, v115
	v_cvt_pk_bf16_f32 v109, v116, v117
	v_cvt_pk_bf16_f32 v90, v102, v103
	v_cvt_pk_bf16_f32 v91, v104, v105
	v_cvt_pk_bf16_f32 v92, v98, v99
	v_cvt_pk_bf16_f32 v93, v100, v101
	global_store_dwordx4 v[94:95], v[78:81], off offset:256
	v_cvt_pk_bf16_f32 v76, v82, v83
	v_cvt_pk_bf16_f32 v77, v84, v85
	v_lshl_add_u64 v[78:79], v[148:149], 0, v[74:75]
	v_cvt_pk_bf16_f32 v74, v86, v87
	v_cvt_pk_bf16_f32 v75, v88, v89
	v_cvt_pk_bf16_f32 v73, v68, v69
	v_cvt_pk_bf16_f32 v65, v60, v61
	v_cvt_pk_bf16_f32 v42, v54, v55
	v_cvt_pk_bf16_f32 v43, v56, v57
	v_cvt_pk_bf16_f32 v44, v50, v51
	v_cvt_pk_bf16_f32 v45, v52, v53
	v_cvt_pk_bf16_f32 v26, v38, v39
	v_cvt_pk_bf16_f32 v27, v40, v41
	v_cvt_pk_bf16_f32 v28, v34, v35
	v_cvt_pk_bf16_f32 v29, v36, v37
	v_lshl_add_u64 v[14:15], v[152:153], 0, s[18:19]
	v_cvt_pk_bf16_f32 v10, v22, v23
	v_cvt_pk_bf16_f32 v11, v24, v25
	v_cvt_pk_bf16_f32 v12, v18, v19
	v_cvt_pk_bf16_f32 v13, v20, v21
	v_cvt_pk_bf16_f32 v6, v6, v7
	v_cvt_pk_bf16_f32 v7, v8, v9
	v_cvt_pk_bf16_f32 v8, v2, v3
	v_cvt_pk_bf16_f32 v9, v4, v5
	s_andn2_b64 vcc, exec, s[24:25]
	s_mov_b64 s[24:25], -1
	global_store_dwordx4 v[152:153], v[126:129], off
	global_store_dwordx4 v[110:111], v[106:109], off
	global_store_dwordx4 v[94:95], v[90:93], off
	global_store_dwordx4 v[78:79], v[74:77], off
	global_store_dwordx4 v[78:79], v[70:73], off offset:256
	global_store_dwordx4 v[58:59], v[62:65], off
	global_store_dwordx4 v[48:49], v[42:45], off
	global_store_dwordx4 v[32:33], v[26:29], off
	global_store_dwordx4 v[16:17], v[10:13], off
	global_store_dwordx4 v[14:15], v[6:9], off offset:256
	s_cbranch_vccnz .LBB0_537
	s_andn2_b64 vcc, exec, s[4:5]
	s_cbranch_vccnz .LBB0_536
	s_branch .LBB0_536
.LBB0_547:
	s_waitcnt vmcnt(0)
	s_and_b64 vcc, exec, s[8:9]
	s_cbranch_vccz .Lnaep_11
	s_barrier
.Lnaep_11:
	s_barrier
.LBB0_548:
	v_readlane_b32 s2, v249, 11
	v_readlane_b32 s3, v249, 12
	s_cmp_eq_u32 s3, 8
	s_cselect_b64 s[2:3], -1, 0
	s_or_b64 s[0:1], s[2:3], s[0:1]
	s_and_b64 vcc, exec, s[0:1]
	s_cbranch_vccnz .LBB0_598
	s_waitcnt vmcnt(0)
	v_cmp_eq_u32_e32 vcc, 0, v0
	s_waitcnt vmcnt(0)
	s_barrier
	s_and_saveexec_b64 s[0:1], vcc
	s_cbranch_execz .LBB0_597
	v_mov_b32_e32 v2, s87
	s_waitcnt vmcnt(0) expcnt(0) lgkmcnt(0)
	ds_read_b32 v4, v2
	ds_read_b32 v2, v2 offset:4
	s_waitcnt lgkmcnt(1)
	v_cmp_ne_u32_e32 vcc, 0, v4
	s_cbranch_vccnz .LBB0_565
	v_readlane_b32 s4, v249, 1
	v_readlane_b32 s5, v249, 2
	s_load_dwordx2 s[2:3], s[4:5], 0x4
	s_add_u32 s4, s82, 0x4200
	s_addc_u32 s5, s83, 0
	s_add_u32 s6, s82, 0x4400
	s_addc_u32 s7, s83, 0
	s_add_u32 s8, s82, 0x4500
	s_addc_u32 s9, s83, 0
	s_add_u32 s10, s82, 0x4600
	s_addc_u32 s11, s83, 0
	s_add_u32 s12, s82, 0x4700
	s_addc_u32 s13, s83, 0
	s_add_u32 s16, s82, 0x4800
	s_addc_u32 s17, s83, 0
	s_add_u32 s18, s82, 0x4900
	s_addc_u32 s19, s83, 0
	s_add_u32 s20, s82, 0x4a00
	s_addc_u32 s21, s83, 0
	s_add_u32 s22, s82, 0x4b00
	s_addc_u32 s23, s83, 0
	s_add_u32 s24, s82, 0x4c00
	s_addc_u32 s25, s83, 0
	s_add_u32 s26, s82, 0x4d00
	s_addc_u32 s27, s83, 0
	s_add_u32 s28, s82, 0x4e00
	s_addc_u32 s29, s83, 0
	s_add_u32 s30, s82, 0x4f00
	s_addc_u32 s31, s83, 0
	s_add_u32 s34, s82, 0x5000
	s_addc_u32 s35, s83, 0
	s_add_u32 s36, s82, 0x5100
	s_addc_u32 s37, s83, 0
	s_add_u32 s38, s82, 0x5200
	s_addc_u32 s39, s83, 0
	s_waitcnt lgkmcnt(0)
	s_mul_i32 s2, s2, s90
	s_add_u32 s40, s82, 0x5300
	s_mul_i32 s2, s2, s3
	s_addc_u32 s41, s83, 0
	s_mov_b32 s3, 1
	v_mov_b32_e32 v18, 0
	s_branch .LBB0_553

.LBB0_693:
	v_lshl_or_b32 v150, s19, 8, v146
	v_lshl_add_u32 v154, s18, 8, v144
	v_ashrrev_i32_e32 v151, 31, v150
	v_lshl_add_u64 v[150:151], v[150:151], 1, s[6:7]
	v_cvt_pk_bf16_f32 v70, v70, v71
	v_cvt_pk_bf16_f32 v71, v72, v73
	v_cvt_pk_bf16_f32 v72, v66, v67
	v_add_u32_e32 v66, 0x80, v154
	v_mad_i64_i32 v[152:153], s[18:19], v154, s45, v[150:151]
	v_cvt_pk_bf16_f32 v110, v110, v111
	v_cvt_pk_bf16_f32 v111, v112, v113
	v_cvt_pk_bf16_f32 v112, v106, v107
	v_cvt_pk_bf16_f32 v113, v108, v109
	v_or_b32_e32 v106, 16, v154
	v_mad_i64_i32 v[66:67], s[18:19], v66, s45, v[150:151]
	v_cvt_pk_bf16_f32 v46, v46, v47
	v_cvt_pk_bf16_f32 v47, v48, v49
	v_cvt_pk_bf16_f32 v48, v42, v43
	v_cvt_pk_bf16_f32 v49, v44, v45
	v_add_u32_e32 v42, 0x90, v154
	global_store_dwordx4 v[152:153], v[110:113], off offset:256
	v_cvt_pk_bf16_f32 v94, v94, v95
	v_cvt_pk_bf16_f32 v95, v96, v97
	v_mad_i64_i32 v[110:111], s[18:19], v106, s45, v[150:151]
	v_cvt_pk_bf16_f32 v96, v90, v91
	v_cvt_pk_bf16_f32 v97, v92, v93
	v_or_b32_e32 v90, 32, v154
	global_store_dwordx4 v[66:67], v[46:49], off offset:256
	v_cvt_pk_bf16_f32 v30, v30, v31
	v_cvt_pk_bf16_f32 v31, v32, v33
	v_mad_i64_i32 v[46:47], s[18:19], v42, s45, v[150:151]
	v_cvt_pk_bf16_f32 v32, v26, v27
	v_cvt_pk_bf16_f32 v33, v28, v29
	v_add_u32_e32 v26, 0xa0, v154
	global_store_dwordx4 v[110:111], v[94:97], off offset:256
	v_cvt_pk_bf16_f32 v78, v78, v79
	v_cvt_pk_bf16_f32 v79, v80, v81
	v_mad_i64_i32 v[94:95], s[18:19], v90, s45, v[150:151]
	v_cvt_pk_bf16_f32 v80, v74, v75
	v_cvt_pk_bf16_f32 v81, v76, v77
	v_or_b32_e32 v74, 48, v154
	global_store_dwordx4 v[46:47], v[30:33], off offset:256
	v_cvt_pk_bf16_f32 v14, v14, v15
	v_cvt_pk_bf16_f32 v15, v16, v17
	v_mad_i64_i32 v[30:31], s[18:19], v26, s45, v[150:151]
	v_cvt_pk_bf16_f32 v16, v10, v11
	v_cvt_pk_bf16_f32 v17, v12, v13
	v_add_u32_e32 v10, 0xb0, v154
	global_store_dwordx4 v[94:95], v[78:81], off offset:256
	global_store_dwordx4 v[30:31], v[14:17], off offset:256
	v_cvt_pk_bf16_f32 v126, v126, v127
	v_mad_i64_i32 v[78:79], s[18:19], v74, s45, v[150:151]
	v_mad_i64_i32 v[14:15], s[18:19], v10, s45, v[150:151]
	v_cvt_pk_bf16_f32 v127, v128, v129
	v_cvt_pk_bf16_f32 v128, v122, v123
	v_cvt_pk_bf16_f32 v129, v124, v125
	v_cvt_pk_bf16_f32 v106, v118, v119
	v_cvt_pk_bf16_f32 v107, v120, v121
	v_cvt_pk_bf16_f32 v108, v114, v115
	v_cvt_pk_bf16_f32 v109, v116, v117
	v_cvt_pk_bf16_f32 v90, v102, v103
	v_cvt_pk_bf16_f32 v91, v104, v105
	v_cvt_pk_bf16_f32 v92, v98, v99
	v_cvt_pk_bf16_f32 v93, v100, v101
	v_cvt_pk_bf16_f32 v74, v86, v87
	v_cvt_pk_bf16_f32 v75, v88, v89
	v_cvt_pk_bf16_f32 v76, v82, v83
	v_cvt_pk_bf16_f32 v77, v84, v85
	v_cvt_pk_bf16_f32 v73, v68, v69
	v_cvt_pk_bf16_f32 v62, v62, v63
	v_cvt_pk_bf16_f32 v63, v64, v65
	v_cvt_pk_bf16_f32 v64, v58, v59
	v_cvt_pk_bf16_f32 v65, v60, v61
	v_cvt_pk_bf16_f32 v42, v54, v55
	v_cvt_pk_bf16_f32 v43, v56, v57
	v_cvt_pk_bf16_f32 v44, v50, v51
	v_cvt_pk_bf16_f32 v45, v52, v53
	v_cvt_pk_bf16_f32 v26, v38, v39
	v_cvt_pk_bf16_f32 v27, v40, v41
	v_cvt_pk_bf16_f32 v28, v34, v35
	v_cvt_pk_bf16_f32 v29, v36, v37
	v_cvt_pk_bf16_f32 v10, v22, v23
	v_cvt_pk_bf16_f32 v11, v24, v25
	v_cvt_pk_bf16_f32 v12, v18, v19
	v_cvt_pk_bf16_f32 v13, v20, v21
	v_cvt_pk_bf16_f32 v6, v6, v7
	v_cvt_pk_bf16_f32 v7, v8, v9
	v_cvt_pk_bf16_f32 v8, v2, v3
	v_cvt_pk_bf16_f32 v9, v4, v5
	s_andn2_b64 vcc, exec, s[20:21]
	s_mov_b64 s[18:19], -1
	global_store_dwordx4 v[152:153], v[126:129], off
	global_store_dwordx4 v[110:111], v[106:109], off
	global_store_dwordx4 v[94:95], v[90:93], off
	global_store_dwordx4 v[78:79], v[74:77], off
	global_store_dwordx4 v[78:79], v[70:73], off offset:256
	global_store_dwordx4 v[66:67], v[62:65], off
	global_store_dwordx4 v[46:47], v[42:45], off
	global_store_dwordx4 v[30:31], v[26:29], off
	global_store_dwordx4 v[14:15], v[10:13], off
	global_store_dwordx4 v[14:15], v[6:9], off offset:256
	s_cbranch_vccnz .LBB0_686
	s_andn2_b64 vcc, exec, s[4:5]
	s_cbranch_vccnz .LBB0_685
	s_branch .LBB0_685
.LBB0_696:
	s_waitcnt vmcnt(0)
	v_readlane_b32 s3, v249, 0
	s_and_b64 vcc, exec, s[10:11]
	s_cbranch_vccz .Lnaep_10
	s_barrier
.Lnaep_10:
	s_barrier
.LBB0_697:
	s_cmpk_gt_i32 s3, 0x1ff
	v_readfirstlane_b32 s9, v0
	s_cbranch_scc1 .LBB0_721
	v_readlane_b32 s3, v249, 0
	s_ashr_i32 s2, s3, 31
	s_lshr_b32 s2, s2, 29
	s_add_i32 s7, s3, s2
	s_and_b32 s2, s7, -8
	s_sub_i32 s2, s3, s2
	s_cmp_gt_i32 s2, -1
	s_cbranch_scc0 .LBB0_700
	s_lshl_b32 s8, s2, 6
	s_cbranch_execz .LBB0_701
	s_branch .LBB0_702

.LBB0_717:
	v_lshl_or_b32 v144, s54, 8, v1
	v_lshl_add_u32 v146, s26, 8, v138
	v_ashrrev_i32_e32 v145, 31, v144
	v_ashrrev_i32_e32 v147, 31, v146
	v_lshl_add_u64 v[144:145], v[144:145], 1, s[72:73]
	v_lshlrev_b64 v[148:149], 12, v[146:147]
	v_lshl_add_u64 v[148:149], v[144:145], 0, v[148:149]
	v_cvt_pk_bf16_f32 v62, v62, v63
	v_cvt_pk_bf16_f32 v63, v64, v65
	v_cvt_pk_bf16_f32 v64, v58, v59
	v_add_co_u32_e32 v58, vcc, s50, v148
	v_cvt_pk_bf16_f32 v70, v70, v71
	v_cvt_pk_bf16_f32 v71, v72, v73
	v_cvt_pk_bf16_f32 v72, v66, v67
	v_lshl_add_u64 v[66:67], v[148:149], 0, s[10:11]
	v_addc_co_u32_e32 v59, vcc, 0, v149, vcc
	v_cvt_pk_bf16_f32 v46, v46, v47
	v_cvt_pk_bf16_f32 v47, v48, v49
	v_cvt_pk_bf16_f32 v48, v42, v43
	v_cvt_pk_bf16_f32 v49, v44, v45
	global_store_dwordx4 v[66:67], v[46:49], off offset:256
	v_cvt_pk_bf16_f32 v110, v110, v111
	v_cvt_pk_bf16_f32 v111, v112, v113
	v_add_co_u32_e32 v48, vcc, s51, v148
	v_cvt_pk_bf16_f32 v112, v106, v107
	v_or_b32_e32 v106, 16, v146
	v_lshl_add_u64 v[46:47], v[148:149], 0, s[12:13]
	v_addc_co_u32_e32 v49, vcc, 0, v149, vcc
	v_cvt_pk_bf16_f32 v30, v30, v31
	v_cvt_pk_bf16_f32 v31, v32, v33
	v_cvt_pk_bf16_f32 v32, v26, v27
	v_cvt_pk_bf16_f32 v33, v28, v29
	v_ashrrev_i32_e32 v107, 31, v106
	v_cvt_pk_bf16_f32 v94, v94, v95
	v_cvt_pk_bf16_f32 v95, v96, v97
	v_cvt_pk_bf16_f32 v96, v90, v91
	v_or_b32_e32 v90, 32, v146
	global_store_dwordx4 v[46:47], v[30:33], off offset:256
	v_cvt_pk_bf16_f32 v113, v108, v109
	v_lshlrev_b64 v[106:107], 12, v[106:107]
	v_add_co_u32_e32 v32, vcc, s52, v148
	v_ashrrev_i32_e32 v91, 31, v90
	v_cvt_pk_bf16_f32 v78, v78, v79
	v_cvt_pk_bf16_f32 v79, v80, v81
	v_cvt_pk_bf16_f32 v80, v74, v75
	v_or_b32_e32 v74, 48, v146
	v_lshl_add_u64 v[30:31], v[148:149], 0, s[16:17]
	v_addc_co_u32_e32 v33, vcc, 0, v149, vcc
	v_cvt_pk_bf16_f32 v14, v14, v15
	v_cvt_pk_bf16_f32 v15, v16, v17
	v_cvt_pk_bf16_f32 v16, v10, v11
	v_cvt_pk_bf16_f32 v17, v12, v13
	global_store_dwordx4 v[148:149], v[110:113], off offset:256
	v_cvt_pk_bf16_f32 v97, v92, v93
	v_lshlrev_b64 v[90:91], 12, v[90:91]
	v_lshl_add_u64 v[110:111], v[144:145], 0, v[106:107]
	v_ashrrev_i32_e32 v75, 31, v74
	global_store_dwordx4 v[30:31], v[14:17], off offset:256
	global_store_dwordx4 v[110:111], v[94:97], off offset:256
	v_cvt_pk_bf16_f32 v81, v76, v77
	v_add_co_u32_e32 v16, vcc, s53, v148
	v_lshl_add_u64 v[94:95], v[144:145], 0, v[90:91]
	v_lshlrev_b64 v[74:75], 12, v[74:75]
	v_addc_co_u32_e32 v17, vcc, 0, v149, vcc
	v_cvt_pk_bf16_f32 v126, v126, v127
	v_cvt_pk_bf16_f32 v127, v128, v129
	v_cvt_pk_bf16_f32 v128, v122, v123
	v_cvt_pk_bf16_f32 v129, v124, v125
	v_cvt_pk_bf16_f32 v106, v118, v119
	v_cvt_pk_bf16_f32 v107, v120, v121
	v_cvt_pk_bf16_f32 v108, v114, v115
	v_cvt_pk_bf16_f32 v109, v116, v117
	v_cvt_pk_bf16_f32 v90, v102, v103
	v_cvt_pk_bf16_f32 v91, v104, v105
	v_cvt_pk_bf16_f32 v92, v98, v99
	v_cvt_pk_bf16_f32 v93, v100, v101
	global_store_dwordx4 v[94:95], v[78:81], off offset:256
	v_cvt_pk_bf16_f32 v76, v82, v83
	v_cvt_pk_bf16_f32 v77, v84, v85
	v_lshl_add_u64 v[78:79], v[144:145], 0, v[74:75]
	v_cvt_pk_bf16_f32 v74, v86, v87
	v_cvt_pk_bf16_f32 v75, v88, v89
	v_cvt_pk_bf16_f32 v73, v68, v69
	v_cvt_pk_bf16_f32 v65, v60, v61
	v_cvt_pk_bf16_f32 v42, v54, v55
	v_cvt_pk_bf16_f32 v43, v56, v57
	v_cvt_pk_bf16_f32 v44, v50, v51
	v_cvt_pk_bf16_f32 v45, v52, v53
	v_cvt_pk_bf16_f32 v26, v38, v39
	v_cvt_pk_bf16_f32 v27, v40, v41
	v_cvt_pk_bf16_f32 v28, v34, v35
	v_cvt_pk_bf16_f32 v29, v36, v37
	v_lshl_add_u64 v[14:15], v[148:149], 0, s[18:19]
	v_cvt_pk_bf16_f32 v10, v22, v23
	v_cvt_pk_bf16_f32 v11, v24, v25
	v_cvt_pk_bf16_f32 v12, v18, v19
	v_cvt_pk_bf16_f32 v13, v20, v21
	v_cvt_pk_bf16_f32 v6, v6, v7
	v_cvt_pk_bf16_f32 v7, v8, v9
	v_cvt_pk_bf16_f32 v8, v2, v3
	v_cvt_pk_bf16_f32 v9, v4, v5
	s_andn2_b64 vcc, exec, s[22:23]
	s_mov_b64 s[22:23], -1
	global_store_dwordx4 v[148:149], v[126:129], off
	global_store_dwordx4 v[110:111], v[106:109], off
	global_store_dwordx4 v[94:95], v[90:93], off
	global_store_dwordx4 v[78:79], v[74:77], off
	global_store_dwordx4 v[78:79], v[70:73], off offset:256
	global_store_dwordx4 v[58:59], v[62:65], off
	global_store_dwordx4 v[48:49], v[42:45], off
	global_store_dwordx4 v[32:33], v[26:29], off
	global_store_dwordx4 v[16:17], v[10:13], off
	global_store_dwordx4 v[14:15], v[6:9], off offset:256
	s_cbranch_vccnz .LBB0_706
	s_andn2_b64 vcc, exec, s[4:5]
	s_cbranch_vccnz .LBB0_705
	s_branch .LBB0_705

.Lnaep_9:
	s_barrier
.LBB0_721:
	v_readlane_b32 s2, v249, 11
	v_readlane_b32 s3, v249, 12
	s_cmp_eq_u32 s3, 10
	s_cselect_b64 s[2:3], -1, 0
	s_or_b64 s[0:1], s[2:3], s[0:1]
	s_and_b64 vcc, exec, s[0:1]
	s_cbranch_vccnz .LBB0_771
	s_waitcnt vmcnt(0)
	v_cmp_eq_u32_e32 vcc, 0, v0
	s_waitcnt vmcnt(0)
	s_barrier
	s_and_saveexec_b64 s[0:1], vcc
	s_cbranch_execz .LBB0_770
	v_mov_b32_e32 v1, s87
	s_waitcnt vmcnt(0) expcnt(0) lgkmcnt(0)
	ds_read_b32 v3, v1
	ds_read_b32 v1, v1 offset:4
	s_waitcnt lgkmcnt(1)
	v_cmp_ne_u32_e32 vcc, 0, v3
	s_cbranch_vccnz .LBB0_738
	v_readlane_b32 s4, v249, 1
	v_readlane_b32 s5, v249, 2
	s_load_dwordx2 s[2:3], s[4:5], 0x4
	s_add_u32 s4, s82, 0x4200
	s_addc_u32 s5, s83, 0
	s_add_u32 s6, s82, 0x4400
	s_addc_u32 s7, s83, 0
	s_add_u32 s8, s82, 0x4500
	s_addc_u32 s9, s83, 0
	s_add_u32 s10, s82, 0x4600
	s_addc_u32 s11, s83, 0
	s_add_u32 s12, s82, 0x4700
	s_addc_u32 s13, s83, 0
	s_add_u32 s16, s82, 0x4800
	s_addc_u32 s17, s83, 0
	s_add_u32 s18, s82, 0x4900
	s_addc_u32 s19, s83, 0
	s_add_u32 s20, s82, 0x4a00
	s_addc_u32 s21, s83, 0
	s_add_u32 s22, s82, 0x4b00
	s_addc_u32 s23, s83, 0
	s_add_u32 s24, s82, 0x4c00
	s_addc_u32 s25, s83, 0
	s_add_u32 s26, s82, 0x4d00
	s_addc_u32 s27, s83, 0
	s_add_u32 s28, s82, 0x4e00
	s_addc_u32 s29, s83, 0
	s_add_u32 s30, s82, 0x4f00
	s_addc_u32 s31, s83, 0
	s_add_u32 s34, s82, 0x5000
	s_addc_u32 s35, s83, 0
	s_add_u32 s36, s82, 0x5100
	s_addc_u32 s37, s83, 0
	s_add_u32 s38, s82, 0x5200
	s_addc_u32 s39, s83, 0
	s_waitcnt lgkmcnt(0)
	s_mul_i32 s2, s2, s90
	s_add_u32 s40, s82, 0x5300
	s_mul_i32 s2, s2, s3
	s_addc_u32 s41, s83, 0
	s_mov_b32 s3, 1
	v_mov_b32_e32 v17, 0
	s_branch .LBB0_726

.Lpeeldone_3:
	ds_read_b128 v[150:153], v146
	ds_read_b128 v[154:157], v146 offset:1024
	ds_read_b128 v[158:161], v146 offset:2048
	ds_read_b128 v[162:165], v146 offset:3072
	ds_read_b128 v[166:169], v147
	ds_read_b128 v[170:173], v147 offset:1024
	ds_read_b128 v[174:177], v147 offset:2048
	ds_read_b128 v[178:181], v147 offset:3072
	ds_read_b128 v[182:185], v148
	ds_read_b128 v[186:189], v148 offset:1024
	ds_read_b128 v[190:193], v148 offset:2048
	ds_read_b128 v[198:201], v148 offset:3072
	ds_read_b128 v[210:213], v148 offset:4096
	ds_read_b128 v[214:217], v148 offset:5120
	ds_read_b128 v[218:221], v148 offset:6144
	ds_read_b128 v[222:225], v148 offset:7168
	s_and_b64 vcc, exec, s[16:17]
	s_cbranch_vccz .LBB0_1976
.LBB0_1976:
	s_mov_b64 s[28:29], -1
	s_cmp_gt_i32 s6, -1
	v_cvt_pk_bf16_f32 v126, v126, v127
	v_cvt_pk_bf16_f32 v127, v128, v129
	v_cvt_pk_bf16_f32 v128, v122, v123
	v_cvt_pk_bf16_f32 v129, v124, v125
	v_cvt_pk_bf16_f32 v118, v118, v119
	v_cvt_pk_bf16_f32 v119, v120, v121
	v_cvt_pk_bf16_f32 v120, v114, v115
	v_cvt_pk_bf16_f32 v121, v116, v117
	v_cvt_pk_bf16_f32 v110, v110, v111
	v_cvt_pk_bf16_f32 v111, v112, v113
	v_cvt_pk_bf16_f32 v112, v106, v107
	v_cvt_pk_bf16_f32 v113, v108, v109
	v_cvt_pk_bf16_f32 v102, v102, v103
	v_cvt_pk_bf16_f32 v103, v104, v105
	v_cvt_pk_bf16_f32 v104, v98, v99
	v_cvt_pk_bf16_f32 v105, v100, v101
	v_cvt_pk_bf16_f32 v94, v94, v95
	v_cvt_pk_bf16_f32 v95, v96, v97
	v_cvt_pk_bf16_f32 v96, v90, v91
	v_cvt_pk_bf16_f32 v97, v92, v93
	v_cvt_pk_bf16_f32 v86, v86, v87
	v_cvt_pk_bf16_f32 v87, v88, v89
	v_cvt_pk_bf16_f32 v88, v82, v83
	v_cvt_pk_bf16_f32 v89, v84, v85
	v_cvt_pk_bf16_f32 v78, v78, v79
	v_cvt_pk_bf16_f32 v79, v80, v81
	v_cvt_pk_bf16_f32 v80, v74, v75
	v_cvt_pk_bf16_f32 v81, v76, v77
	v_cvt_pk_bf16_f32 v70, v70, v71
	v_cvt_pk_bf16_f32 v71, v72, v73
	v_cvt_pk_bf16_f32 v72, v66, v67
	v_cvt_pk_bf16_f32 v73, v68, v69
	v_cvt_pk_bf16_f32 v62, v62, v63
	v_cvt_pk_bf16_f32 v63, v64, v65
	v_cvt_pk_bf16_f32 v64, v58, v59
	v_cvt_pk_bf16_f32 v65, v60, v61
	v_cvt_pk_bf16_f32 v54, v54, v55
	v_cvt_pk_bf16_f32 v55, v56, v57
	v_cvt_pk_bf16_f32 v56, v50, v51
	v_cvt_pk_bf16_f32 v57, v52, v53
	v_cvt_pk_bf16_f32 v46, v46, v47
	v_cvt_pk_bf16_f32 v47, v48, v49
	v_cvt_pk_bf16_f32 v48, v42, v43
	v_cvt_pk_bf16_f32 v49, v44, v45
	v_cvt_pk_bf16_f32 v38, v38, v39
	v_cvt_pk_bf16_f32 v39, v40, v41
	v_cvt_pk_bf16_f32 v40, v34, v35
	v_cvt_pk_bf16_f32 v41, v36, v37
	v_cvt_pk_bf16_f32 v30, v30, v31
	v_cvt_pk_bf16_f32 v31, v32, v33
	v_cvt_pk_bf16_f32 v32, v26, v27
	v_cvt_pk_bf16_f32 v33, v28, v29
	v_cvt_pk_bf16_f32 v22, v22, v23
	v_cvt_pk_bf16_f32 v23, v24, v25
	v_cvt_pk_bf16_f32 v24, v18, v19
	v_cvt_pk_bf16_f32 v25, v20, v21
	v_cvt_pk_bf16_f32 v14, v14, v15
	v_cvt_pk_bf16_f32 v15, v16, v17
	v_cvt_pk_bf16_f32 v16, v10, v11
	v_cvt_pk_bf16_f32 v17, v12, v13
	v_cvt_pk_bf16_f32 v6, v6, v7
	v_cvt_pk_bf16_f32 v7, v8, v9
	v_cvt_pk_bf16_f32 v8, v2, v3
	v_cvt_pk_bf16_f32 v9, v4, v5
	s_cbranch_scc1 .LBB0_1982
	s_andn2_b64 vcc, exec, s[28:29]
	s_cbranch_vccz .LBB0_1983

.LBB0_1983:
	v_lshl_or_b32 v2, s12, 8, v145
	v_ashrrev_i32_e32 v3, 31, v2
	v_lshl_add_u32 v10, s14, 8, v1
	v_lshl_add_u64 v[2:3], v[2:3], 1, s[78:79]
	v_mad_i64_i32 v[4:5], s[28:29], v10, s64, v[2:3]
	global_store_dwordx4 v[4:5], v[126:129], off
	global_store_dwordx4 v[4:5], v[94:97], off offset:256
	v_or_b32_e32 v4, 16, v10
	v_mad_i64_i32 v[4:5], s[28:29], v4, s64, v[2:3]
	global_store_dwordx4 v[4:5], v[118:121], off
	global_store_dwordx4 v[4:5], v[86:89], off offset:256
	v_or_b32_e32 v4, 32, v10
	v_mad_i64_i32 v[4:5], s[28:29], v4, s64, v[2:3]
	global_store_dwordx4 v[4:5], v[110:113], off
	global_store_dwordx4 v[4:5], v[78:81], off offset:256
	v_or_b32_e32 v4, 48, v10
	v_mad_i64_i32 v[4:5], s[28:29], v4, s64, v[2:3]
	global_store_dwordx4 v[4:5], v[102:105], off
	global_store_dwordx4 v[4:5], v[70:73], off offset:256
	v_add_u32_e32 v4, 0x80, v10
	v_mad_i64_i32 v[4:5], s[28:29], v4, s64, v[2:3]
	global_store_dwordx4 v[4:5], v[62:65], off
	global_store_dwordx4 v[4:5], v[30:33], off offset:256
	v_add_u32_e32 v4, 0x90, v10
	v_mad_i64_i32 v[4:5], s[28:29], v4, s64, v[2:3]
	global_store_dwordx4 v[4:5], v[54:57], off
	global_store_dwordx4 v[4:5], v[22:25], off offset:256
	v_add_u32_e32 v4, 0xa0, v10
	v_mad_i64_i32 v[4:5], s[28:29], v4, s64, v[2:3]
	global_store_dwordx4 v[4:5], v[46:49], off
	global_store_dwordx4 v[4:5], v[14:17], off offset:256
	v_add_u32_e32 v4, 0xb0, v10
	v_mad_i64_i32 v[2:3], s[28:29], v4, s64, v[2:3]
	global_store_dwordx4 v[2:3], v[38:41], off
	global_store_dwordx4 v[2:3], v[6:9], off offset:256
	s_cmp_eq_u32 s13, 2
	s_mov_b64 s[12:13], -1
	s_cbranch_scc1 .LBB0_1962
.LBB0_1984:
	s_andn2_b64 vcc, exec, s[8:9]
	s_cbranch_vccnz .LBB0_1961
	s_branch .LBB0_1961
.LBB0_1986:
	s_waitcnt vmcnt(0)
	s_and_b64 vcc, exec, s[16:17]
	s_cbranch_vccz .Lnaep_3
	s_barrier
.Lnaep_3:
	s_barrier
.LBB0_1987:
	v_readlane_b32 s2, v249, 11
	v_readlane_b32 s3, v249, 12
	s_cmp_eq_u32 s3, 26
	s_cselect_b64 s[2:3], -1, 0
	s_or_b64 s[0:1], s[2:3], s[0:1]
	s_and_b64 vcc, exec, s[0:1]
	s_cbranch_vccnz .LBB0_2037
	s_waitcnt vmcnt(0)
	v_cmp_eq_u32_e32 vcc, 0, v0
	s_waitcnt vmcnt(0)
	s_barrier
	s_and_saveexec_b64 s[0:1], vcc
	s_cbranch_execz .LBB0_2036
	v_mov_b32_e32 v1, s87
	s_waitcnt vmcnt(0) expcnt(0) lgkmcnt(0)
	ds_read_b32 v3, v1
	ds_read_b32 v1, v1 offset:4
	s_waitcnt lgkmcnt(1)
	v_cmp_ne_u32_e32 vcc, 0, v3
	s_cbranch_vccnz .LBB0_2004
	v_readlane_b32 s4, v249, 1
	v_readlane_b32 s5, v249, 2
	s_load_dwordx2 s[2:3], s[4:5], 0x4
	s_add_u32 s4, s82, 0x4200
	s_addc_u32 s5, s83, 0
	s_add_u32 s6, s82, 0x4400
	s_addc_u32 s7, s83, 0
	s_add_u32 s8, s82, 0x4500
	s_addc_u32 s9, s83, 0
	s_add_u32 s10, s82, 0x4600
	s_addc_u32 s11, s83, 0
	s_add_u32 s12, s82, 0x4700
	s_addc_u32 s13, s83, 0
	s_add_u32 s14, s82, 0x4800
	s_addc_u32 s15, s83, 0
	s_add_u32 s16, s82, 0x4900
	s_addc_u32 s17, s83, 0
	s_add_u32 s18, s82, 0x4a00
	s_addc_u32 s19, s83, 0
	s_add_u32 s20, s82, 0x4b00
	s_addc_u32 s21, s83, 0
	s_add_u32 s22, s82, 0x4c00
	s_addc_u32 s23, s83, 0
	s_add_u32 s24, s82, 0x4d00
	s_addc_u32 s25, s83, 0
	s_add_u32 s26, s82, 0x4e00
	s_addc_u32 s27, s83, 0
	s_add_u32 s28, s82, 0x4f00
	s_addc_u32 s29, s83, 0
	s_add_u32 s30, s82, 0x5000
	s_addc_u32 s31, s83, 0
	s_add_u32 s34, s82, 0x5100
	s_addc_u32 s35, s83, 0
	s_add_u32 s36, s82, 0x5200
	s_addc_u32 s37, s83, 0
	s_waitcnt lgkmcnt(0)
	s_mul_i32 s2, s2, s90
	s_add_u32 s38, s82, 0x5300
	s_mul_i32 s2, s2, s3
	s_addc_u32 s39, s83, 0
	s_mov_b32 s3, 1
	v_mov_b32_e32 v17, 0
	s_branch .LBB0_1992
